# stick-breaking early-exit bound -150 -> -134 (log2): weights below 2^-134 round to zero in the bf16 P operand, outputs bit-identical
# speedup vs baseline: 1.0083x; 1.0083x over previous
; #define LAS __attribute__((address_space(3)))
; #define S_LOAD(key0) do { st0 = *(const u32x4*)(kg + (size_t)(key0) * 1024); st1 = *(const u32x4*)(kg + (size_t)((key0) + 64) * 1024); st2 = *(const u32x4*)(vg + (size_t)(key0) * 1024); st3 = *(const u32x4*)(vg + (size_t)((key0) + 64) * 1024); } while (0)
; #define S_STORE(buf) do { *(LAS u32x4*)(lds + klds + (buf) * SK_BUF) = st0; *(LAS u32x4*)(lds + klds + (buf) * SK_BUF + 64 * SK_STR) = st1; \
;         *(LAS u32x4*)(lds + vlds + (buf) * SV_BUF) = st2; *(LAS u32x4*)(lds + vlds + (buf) * SV_BUF + 64 * SV_STR) = st3; } while (0)
; __device__ __forceinline__ void sb_unit(const Frame& F, int b, int hd, int qi, int dry) {
;     ...
;     const int srow = tid >> 3, sc16 = tid & 7;
;     const bf16* kg = KB + (rowbase + srow) * 1024 + 64 * hd + sc16 * 8;
;     const bf16* vg = VB + (rowbase + srow) * 1024 + 64 * hd + sc16 * 8;
;     const int klds = S_KOFF + srow * SK_STR + sc16 * 16, vlds = S_VOFF + srow * SV_STR + sc16 * 16;
;     u32x4 st0, st1, st2, st3;
;     ...
;     const int jmax = 2 * qi + 1, nt = jmax + 2;
;     __syncthreads();
;     S_LOAD(NMETA + 128 * jmax); S_STORE(0);
;     __syncthreads();
;     f32x16 O[2];
; #pragma unroll
;     for (int dt = 0; dt < 2; ++dt)
; #pragma unroll
;         for (int r = 0; r < 16; ++r) O[dt][r] = 0.f;
;     float C = 0.f;
;     bool dead = false;
;     constexpr float SB_DEAD = -150.0f;
;     LAS int* flags = (LAS int*)(lds + S_VOFF + 2 * SV_BUF);
;     const int kra = S_KOFF + r32 * SK_STR + hi * 16;
;     const int vra = S_VOFF + (4 * hi + ((lane & 15) >> 2)) * SV_STR + (16 * ((lane >> 4) & 1) + 4 * (lane & 3)) * 2;
;     for (int it = 0; it < nt; ++it) {
;         const bool meta = (it > jmax);
;         const int key0 = meta ? 0 : NMETA + 128 * (jmax - it);
;         if (it + 1 < nt) { const int nk = (it + 1 > jmax) ? 0 : NMETA + 128 * (jmax - it - 1); S_LOAD(nk); }
;         if (!dead && (meta || key0 < tqw + 31)) {
;             const LAS unsigned char* kb = lds + kra + (it & 1) * SK_BUF;
;             const LAS unsigned char* vb = lds + vra + (it & 1) * SV_BUF;
.LBB0_330:
	s_mov_b32 s60, 0x42fc0000
	v_readlane_b32 s85, v254, 55
	v_readlane_b32 s80, v254, 57
	s_lshl_b32 s20, s85, 5
	v_readlane_b32 s82, v254, 59
	v_readlane_b32 s83, v254, 60
	s_add_u32 s6, s82, 0xef00000
	s_addc_u32 s7, s83, 0
	s_add_u32 s8, s82, 0x13000000
	s_addc_u32 s9, s83, 0
	s_add_u32 s12, s82, 0x17100000
	s_addc_u32 s13, s83, 0
	v_lshrrev_b32_e32 v96, 3, v177
	v_and_b32_e32 v1, 7, v177
	s_lshl_b32 s1, s85, 2
	s_add_i32 s10, 0, 0x15000
	v_mul_u32_u24_e32 v2, 0x90, v96
	v_lshlrev_b32_e32 v3, 4, v1
	s_add_i32 s21, s10, s1
	s_mul_i32 s1, s85, 0x1200
	s_waitcnt vmcnt(2)
	v_add3_u32 v116, 0, v2, v3
	v_mul_u32_u24_e32 v2, 0x90, v204
	s_add_i32 s1, s1, 0
	v_lshlrev_b32_e32 v0, 3, v1
	s_movk_i32 s0, 0x90
	v_mul_u32_u24_e32 v4, 0xc0, v207
	v_add3_u32 v118, 0, v2, v156
	s_waitcnt vmcnt(1)
	v_lshl_add_u32 v120, v1, 2, s10
	v_mov_b32_e32 v1, s1
	v_add_u32_e32 v2, s1, v3
	v_lshrrev_b32_e32 v3, 3, v176
	v_mov_b32_e32 v99, 0
	v_add3_u32 v119, 0, v4, v208
	v_mad_u32_u24 v1, v204, s0, v1
	v_mul_u32_u24_e32 v4, 0x90, v3
	v_lshlrev_b32_e32 v100, 11, v3
	v_readlane_b32 s77, v254, 62
	v_readlane_b32 s78, v254, 45
	v_readlane_b32 s86, v254, 43
	v_readlane_b32 s81, v254, 58
	v_mov_b32_e32 v97, v99
	s_mov_b32 s15, 0
	v_mad_u32_u24 v117, v96, 48, v116
	v_cmp_gt_u32_e64 s[2:3], 32, v176
	v_cmp_eq_u32_e64 s[4:5], 0, v176
	v_mov_b32_e32 v101, v99
	v_or_b32_e32 v102, 0x4000, v100
	v_mov_b32_e32 v103, v99
	v_or_b32_e32 v104, 0x8000, v100
	v_mov_b32_e32 v105, v99
	v_or_b32_e32 v106, 0xc000, v100
	v_mov_b32_e32 v107, v99
	v_mov_b32_e32 v121, 0x1010
	v_mov_b32_e32 v108, v152
	v_mov_b32_e32 v109, v99
	v_lshlrev_b32_e32 v98, 1, v0
	s_mov_b32 s22, 0xc3060000
	v_add_u32_e32 v122, v1, v154
	v_add_u32_e32 v123, v2, v4
	s_mov_b32 s23, s77
	s_mov_b32 s24, s77
	v_readlane_b32 s79, v254, 46
	v_readlane_b32 s87, v254, 44
	v_readlane_b32 s88, v254, 42
	v_readlane_b32 s89, v254, 41
	v_readlane_b32 s91, v254, 40
	s_branch .LBB0_332
